# v5 (aligned) plus static s_setprio 2 for the two score waves inside P4 decode-attention units
# baseline (speedup 1.0000x reference)
.LBB0_787:
	s_or_b64 exec, exec, s[12:13]
	s_setprio 0
	s_mov_b64 s[10:11], 0
	s_barrier

.LBB0_793:
	s_or_b64 exec, exec, s[10:11]
	s_waitcnt vmcnt(0) lgkmcnt(0)
	s_barrier
	ds_read_b32 v0, v123
	s_movk_i32 s10, 0x7f
	s_waitcnt lgkmcnt(0)
	s_barrier
	v_cmp_lt_i32_e32 vcc, s10, v0
	v_readfirstlane_b32 s18, v0
	s_mov_b64 s[10:11], -1
	s_cbranch_vccnz .LBB0_788
	v_readfirstlane_b32 s99, v186
	s_cmpk_lt_u32 s99, 0x80
	s_cbranch_scc0 .Lmy_dc_noprio
	s_setprio 2
.Lmy_dc_noprio:
	v_mov_b32_e32 v140, v186
	s_lshl_b32 s10, s18, 2
	s_add_i32 s70, s10, 0x8000
	v_ashrrev_i32_e32 v6, 7, v140
	v_bfe_u32 v7, v140, 4, 3
	v_add_u32_e32 v2, s70, v6
	v_mov_b64_e32 v[0:1], s[30:31]
	v_and_b32_e32 v36, 15, v140
	v_mad_i64_i32 v[0:1], s[10:11], v2, s95, v[0:1]
	v_mul_u32_u24_e32 v2, 0x60, v7
	v_lshlrev_b32_e32 v120, 1, v2
	v_lshl_or_b32 v4, v6, 5, v36
	v_lshl_add_u64 v[0:1], v[0:1], 0, v[120:121]
	v_lshlrev_b32_e32 v120, 1, v36
	v_add_u32_e32 v2, 0x10200, v4
	v_add_u32_e32 v4, 0x10210, v4
	v_lshl_add_u64 v[0:1], v[0:1], 0, v[120:121]
	v_ashrrev_i32_e32 v3, 31, v2
	v_ashrrev_i32_e32 v5, 31, v4
	v_lshl_add_u64 v[2:3], v[2:3], 2, s[52:53]
	v_lshl_add_u64 v[4:5], v[4:5], 2, s[52:53]
	global_load_ushort v16, v[0:1], off offset:128
	global_load_ushort v17, v[0:1], off offset:160
	global_load_dword v34, v[2:3], off
	global_load_dword v35, v[4:5], off
	v_lshl_or_b32 v0, v6, 3, v7
	s_movk_i32 s10, 0x250
	v_mul_lo_u32 v0, v0, s10
	v_bfe_u32 v122, v140, 5, 1
	v_add3_u32 v38, 0, v0, v120
	v_and_or_b32 v2, v140, 3, s70
	v_mov_b64_e32 v[0:1], s[56:57]
	v_mad_i64_i32 v[0:1], s[10:11], v2, s95, v[0:1]
	v_lshlrev_b32_e32 v120, 4, v122
	v_lshl_add_u64 v[12:13], v[0:1], 0, v[120:121]
	global_load_dwordx4 v[0:3], v[12:13], off
	global_load_dwordx4 v[4:7], v[12:13], off offset:32
	global_load_dwordx4 v[8:11], v[12:13], off offset:64
	s_nop 0
	global_load_dwordx4 v[12:15], v[12:13], off offset:96
	s_load_dwordx2 s[12:13], s[0:1], 0x88
	v_and_b32_e32 v139, 31, v140
	v_and_b32_e32 v18, 32, v140
	v_lshl_or_b32 v120, v139, 11, v18
	v_and_b32_e32 v141, 63, v140
	s_waitcnt lgkmcnt(0)
	s_add_u32 s12, s12, s64
	s_addc_u32 s13, s13, s65
	v_lshl_add_u64 v[32:33], s[12:13], 0, v[120:121]
	v_cmp_lt_u32_e64 s[12:13], 3, v139
	v_cmp_gt_u32_e64 s[10:11], 32, v141
	v_lshl_add_u32 v37, v139, 1, s90
	s_mov_b64 s[14:15], 0
	s_waitcnt vmcnt(7)
	v_lshlrev_b32_e32 v39, 16, v16
	s_waitcnt vmcnt(6)
	v_lshlrev_b32_e32 v16, 16, v17
	s_waitcnt vmcnt(5)
	v_mul_f32_e32 v41, v34, v16
	s_waitcnt vmcnt(4)
	v_mul_f32_e32 v40, v35, v16
	v_fmac_f32_e32 v41, v35, v39
	s_waitcnt vmcnt(3)
	v_cndmask_b32_e64 v16, v0, 0, s[12:13]
	v_fma_f32 v0, v34, v39, -v40
	v_mul_f32_e32 v0, 0x3e16c740, v0
	v_cndmask_b32_e64 v18, v2, 0, s[12:13]
	v_cndmask_b32_e64 v17, v1, 0, s[12:13]
	v_mul_f32_e32 v1, 0x3e16c740, v41
	v_bfe_u32 v2, v0, 16, 1
	v_cndmask_b32_e64 v19, v3, 0, s[12:13]
	s_waitcnt vmcnt(2)
	v_cndmask_b32_e64 v23, v7, 0, s[12:13]
	v_cndmask_b32_e64 v22, v6, 0, s[12:13]
	v_cndmask_b32_e64 v21, v5, 0, s[12:13]
	v_cndmask_b32_e64 v20, v4, 0, s[12:13]
	s_waitcnt vmcnt(1)
	v_cndmask_b32_e64 v27, v11, 0, s[12:13]
	v_cndmask_b32_e64 v26, v10, 0, s[12:13]
	v_cndmask_b32_e64 v25, v9, 0, s[12:13]
	v_cndmask_b32_e64 v24, v8, 0, s[12:13]
	s_waitcnt vmcnt(0)
	v_cndmask_b32_e64 v31, v15, 0, s[12:13]
	v_cndmask_b32_e64 v30, v14, 0, s[12:13]
	v_cndmask_b32_e64 v29, v13, 0, s[12:13]
	v_cndmask_b32_e64 v28, v12, 0, s[12:13]
	v_bfe_u32 v3, v1, 16, 1
	v_add3_u32 v0, v0, v2, s96
	v_add3_u32 v1, v1, v3, s96
	ds_write_b16_d16_hi v38, v0 offset:512
	ds_write_b16_d16_hi v38, v1 offset:544
	s_branch .LBB0_796
